# static s_setprio 1 for waves 4-7 during the NA2 phase (same-program wave pairs, one barrier per block), reset to 0 at mlA entry
# speedup vs baseline: 1.0125x; 1.0075x over previous
; #define TIDX (opaque_tid())
; __device__ void ph_na2(const P& p, LAS unsigned char* lds) {
;     ...
;     const int tid = TIDX, lane = tid & 63, w = __builtin_amdgcn_readfirstlane(tid >> 6), c = lane & 15, g = lane >> 4, qb = w & 3, ur = w >> 2;
;     const int qq = (lane & 15) >> 2, pp = lane & 3;
;     const int per = (4096 + gridDim.x - 1) / gridDim.x;
;     const int u_lo = blockIdx.x * per, u_hi = min(u_lo + per, 4096);
;     int last_bh = -1, have_hi = -1;
;     const int cstart = (qb == 0) ? 0 : (qb == 1) ? 8 : (qb == 2) ? 24 : 32;
.LBB0_303:
	s_andn2_b64 vcc, exec, s[0:1]
	s_cbranch_vccnz .LBB0_517
	s_waitcnt vmcnt(0) lgkmcnt(0)
	v_mov_b32_e32 v2, v169
	s_nop 0
	v_readfirstlane_b32 s5, v2
	s_bfe_u32 s3, s5, 0x20006
	s_bitcmp1_b32 s5, 8
	s_cbranch_scc0 .Lna_prio_skip
	s_setprio 1
.Lna_prio_skip:
	s_cmp_lt_i32 s3, 1
	s_mov_b32 s4, s3
	s_cbranch_scc1 .LBB0_309
	s_cmp_eq_u32 s3, 1
	s_mov_b64 s[0:1], -1
	s_cbranch_scc1 .LBB0_307
	s_cmp_eq_u32 s3, 2
	s_cselect_b32 s4, 24, 32
	s_mov_b64 s[0:1], 0

; #define TIDX (opaque_tid())
; __device__ void ph_mlA(const P& p, LAS unsigned char* lds) {
;     ...
;     const int tid = TIDX, lane = tid & 63, w = __builtin_amdgcn_readfirstlane(tid >> 6), c = lane & 15, g = lane >> 4, qq = (lane & 15) >> 2, pp = lane & 3;
;     const int ch = tid & 15, rb = tid >> 4;
;     u32x4 kr[4], vr[4]; float gi0 = 0.f, gf0 = 0.f, gi1 = 0.f, gf1 = 0.f;
;     ...
;     int slot = blockIdx.x;
;     if (slot < NSLOT) MLA_PREFETCH(slot)
; __device__ __forceinline__ void run_phase(const P& p, int ph_in, bool second, LAS unsigned char* lds) {
;     ...
;         __syncthreads();
.LBB0_419:
	s_setprio 0
	v_readlane_b32 s4, v250, 27
	v_readlane_b32 s5, v250, 28
	v_mov_b32_e32 v36, v169
	v_mov_b32_e32 v91, 0
	v_cndmask_b32_e64 v0, 0, 1, s[4:5]
	s_waitcnt vmcnt(0)
	s_barrier
	v_cmp_ne_u32_e64 s[0:1], 1, v0
	v_and_b32_e32 v34, 63, v36
	v_readfirstlane_b32 s3, v36
	v_and_b32_e32 v35, 15, v36
	v_ashrrev_i32_e32 v98, 4, v36
	s_andn2_b64 vcc, exec, s[4:5]
	v_mov_b32_e32 v90, v91
	v_mov_b32_e32 v93, v91
	v_mov_b32_e32 v92, v91
	s_cbranch_vccnz .LBB0_422
	v_readlane_b32 s4, v251, 25
	v_lshlrev_b32_e32 v0, 4, v35
	s_mov_b64 s[8:9], 0x8000
	v_add_u32_e32 v2, s4, v98
	v_ashrrev_i32_e32 v3, 31, v2
	v_lshlrev_b64 v[26:27], 10, v[2:3]
	v_readlane_b32 s4, v253, 13
	v_readlane_b32 s6, v250, 11
	v_readlane_b32 s7, v250, 12
	v_or3_b32 v26, v0, s4, v26
	v_readlane_b32 s4, v250, 9
	v_lshl_add_u64 v[10:11], v[26:27], 0, s[8:9]
	s_mov_b64 s[8:9], 0x10000
	v_readlane_b32 s5, v250, 10
	v_lshl_add_u64 v[18:19], v[26:27], 0, s[8:9]
	s_mov_b64 s[8:9], 0x18000
	v_lshl_add_u64 v[2:3], s[4:5], 0, v[26:27]
	v_lshl_add_u64 v[4:5], s[6:7], 0, v[26:27]
	v_lshl_add_u64 v[26:27], v[26:27], 0, s[8:9]
	v_lshl_add_u64 v[12:13], s[4:5], 0, v[10:11]
	v_lshl_add_u64 v[10:11], s[6:7], 0, v[10:11]
	v_lshl_add_u64 v[20:21], s[4:5], 0, v[18:19]
	v_lshl_add_u64 v[18:19], s[6:7], 0, v[18:19]
	v_lshl_add_u64 v[28:29], s[4:5], 0, v[26:27]
	v_lshl_add_u64 v[26:27], s[6:7], 0, v[26:27]
	global_load_dwordx4 v[6:9], v[2:3], off
	s_nop 0
	global_load_dwordx4 v[2:5], v[4:5], off
	s_nop 0
	global_load_dwordx4 v[14:17], v[12:13], off
	s_nop 0
	global_load_dwordx4 v[10:13], v[10:11], off
	s_nop 0
	global_load_dwordx4 v[22:25], v[20:21], off
	s_nop 0
	global_load_dwordx4 v[18:21], v[18:19], off
	s_nop 0
	global_load_dwordx4 v[30:33], v[28:29], off
	s_nop 0
	global_load_dwordx4 v[26:29], v[26:27], off
	v_mov_b32_e32 v92, 0
	s_cmp_gt_u32 s3, 63
	v_mov_b32_e32 v93, 0
	v_mov_b32_e32 v90, 0
	v_mov_b32_e32 v91, 0
	s_cbranch_scc1 .LBB0_422
	v_lshlrev_b32_e32 v0, 1, v34
	v_readlane_b32 s4, v250, 29
	v_xor_b32_e32 v37, 0x7f, v0
	v_readlane_b32 s5, v250, 30
	v_xor_b32_e32 v38, 0x7e, v0
	v_readlane_b32 s6, v251, 25
	v_cndmask_b32_e64 v37, v37, v0, s[4:5]
	v_or_b32_e32 v0, 1, v0
	v_cndmask_b32_e64 v0, v38, v0, s[4:5]
	v_or_b32_e32 v38, s6, v37
	v_ashrrev_i32_e32 v39, 31, v38
	v_readlane_b32 s4, v250, 33
	v_or_b32_e32 v40, s6, v0
	v_lshlrev_b64 v[38:39], 6, v[38:39]
	v_readlane_b32 s5, v250, 34
	v_ashrrev_i32_e32 v41, 31, v40
	v_lshlrev_b64 v[40:41], 6, v[40:41]
	v_lshl_add_u64 v[38:39], s[4:5], 0, v[38:39]
	v_lshl_add_u64 v[40:41], s[4:5], 0, v[40:41]
	global_load_dwordx2 v[92:93], v[38:39], off
	global_load_dwordx2 v[90:91], v[40:41], off
